# attention K tile staged by LDS-DMA (global_load_lds_dwordx4, 25 x 1KB per tile) instead of VGPR + ds_write_b128; V still register-staged
# speedup vs baseline: 1.0074x; 1.0074x over previous
; #define AT_LOAD(t) do { const bf16_t* kn_ = knp + (size_t)(t) * 65536; kreg[0] = *(const u32x4*)(kn_); kreg[1] = *(const u32x4*)(kn_ + 64); kreg[2] = *(const u32x4*)(krp + (size_t)(t) * 4096); \
;                         const bf16_t* vt_ = vtp + (size_t)(t) * 65536; vreg[0] = *(const u32x4*)(vt_); vreg[1] = *(const u32x4*)(vt_ + 4096); } while (0)
; #define AT_STORE(buf) do { ldsp base_ = lds + (buf) * AT_BUF; *(LAS u32x4*)(base_ + kdst) = kreg[0]; *(LAS u32x4*)(base_ + kdst + 128) = kreg[1]; *(LAS u32x4*)(base_ + kdst + 256) = kreg[2]; \
;                            lds_w8x2(base_ + vdst, vreg[0]); lds_w8x2(base_ + vdst + 64 * AT_VP, vreg[1]); } while (0)
; DI void attn_phase(ldsp lds, const bf16_t* Q, const bf16_t* KN, const bf16_t* KR, const bf16_t* VT, bf16_t* O, int vcu, int G) {
;     ...
;             bf16x8 qf[12];
;             { const bf16_t* qp = Q + (tok0 + q0 + l31) * 1536 + h * 192 + hh * 8;
; #pragma unroll
;               for (int ks = 0; ks < 12; ++ks) qf[ks] = *(const bf16x8*)(qp + ks * 16); }
;             f32x16 o[4];
; #pragma unroll
;             for (int d = 0; d < 4; ++d)
; #pragma unroll
;                 for (int r = 0; r < 16; ++r) o[d][r] = 0.f;
;             float mrun = -1e30f, lrun = 0.f;
;             const int ntiles = (qb + 1) * 4;
;             u32x4 kreg[3], vreg[2];
;             const int srow = tid >> 3, scp = tid & 7;
;             const bf16_t* knp = KN + (tok0 + srow) * 1024 + h * 128 + scp * 8;
;             const bf16_t* krp = KR + (tok0 + srow) * 64 + scp * 8;
;             const bf16_t* vtp = VT + ((tok0 >> 6) * 1024 + h * 128 + srow) * 64 + scp * 8;
;             const int kdst = srow * AT_KP + scp * 16, vdst = AT_VOFF + srow * AT_VP + scp * 16;
;     ...
;             AT_LOAD(0); AT_STORE(0); __syncthreads();
.LBB0_1448:
	s_xor_b64 s[12:13], s[14:15], -1
	s_and_b64 s[14:15], s[14:15], exec
	s_cselect_b32 s24, s23, s22
	s_lshl_b32 s25, s24, 8
	s_add_i32 s14, s25, s0
	s_ashr_i32 s15, s14, 31
	v_lshl_add_u64 v[218:219], v[198:199], 0, s[14:15]
	v_mad_u64_u32 v[2:3], s[16:17], v218, s1, v[200:201]
	v_mad_i32_i24 v3, v219, s1, v3
	v_and_b32_e32 v1, 63, v192
	s_lshl_b32 s99, s0, 1
	v_add_u32_e32 v1, s99, v1
	v_lshlrev_b32_e32 v66, 11, v174
	v_add_u32_e32 v66, v66, v176
	v_sub_co_u32_e32 v68, vcc, v202, v66
	s_nop 1
	v_subbrev_co_u32_e32 v69, vcc, 0, v203, vcc
	v_lshlrev_b32_e32 v66, 7, v174
	v_add_u32_e32 v66, v66, v176
	v_sub_co_u32_e32 v70, vcc, v204, v66
	s_nop 1
	v_subbrev_co_u32_e32 v71, vcc, 0, v205, vcc
	s_mov_b32 s99, 0xa3d70a4
	v_mov_b32_e32 v78, 0x2000
	v_mov_b32_e32 v79, 0x20000
	v_add_u32_e32 v72, 0, v1
	v_mul_hi_u32 v73, v72, s99
	v_mul_u32_u24_e32 v74, 25, v73
	v_sub_u32_e32 v74, v72, v74
	v_cmp_eq_u32_e32 vcc, 24, v74
	s_nop 1
	v_cndmask_b32_e64 v74, v74, 0, vcc
	v_cmp_lt_u32_e32 vcc, 15, v74
	v_lshlrev_b32_e32 v75, 11, v73
	v_lshl_add_u32 v75, v74, 4, v75
	v_lshlrev_b32_e32 v76, 7, v73
	v_lshl_add_u32 v76, v74, 4, v76
	v_add_u32_e32 v76, 0xffffff00, v76
	v_cndmask_b32_e32 v75, v75, v76, vcc
	v_cndmask_b32_e32 v76, v68, v70, vcc
	v_cndmask_b32_e32 v77, v69, v71, vcc
	v_cndmask_b32_e32 v134, v79, v78, vcc
	v_add_co_u32_e32 v106, vcc, v76, v75
	s_nop 1
	v_addc_co_u32_e32 v107, vcc, 0, v77, vcc
	v_add_u32_e32 v72, 512, v1
	v_mul_hi_u32 v73, v72, s99
	v_mul_u32_u24_e32 v74, 25, v73
	v_sub_u32_e32 v74, v72, v74
	v_cmp_eq_u32_e32 vcc, 24, v74
	s_nop 1
	v_cndmask_b32_e64 v74, v74, 0, vcc
	v_cmp_lt_u32_e32 vcc, 15, v74
	v_lshlrev_b32_e32 v75, 11, v73
	v_lshl_add_u32 v75, v74, 4, v75
	v_lshlrev_b32_e32 v76, 7, v73
	v_lshl_add_u32 v76, v74, 4, v76
	v_add_u32_e32 v76, 0xffffff00, v76
	v_cndmask_b32_e32 v75, v75, v76, vcc
	v_cndmask_b32_e32 v76, v68, v70, vcc
	v_cndmask_b32_e32 v77, v69, v71, vcc
	v_cndmask_b32_e32 v135, v79, v78, vcc
	v_add_co_u32_e32 v108, vcc, v76, v75
	s_nop 1
	v_addc_co_u32_e32 v109, vcc, 0, v77, vcc
	v_add_u32_e32 v72, 1024, v1
	v_mul_hi_u32 v73, v72, s99
	v_mul_u32_u24_e32 v74, 25, v73
	v_sub_u32_e32 v74, v72, v74
	v_cmp_eq_u32_e32 vcc, 24, v74
	s_nop 1
	v_cndmask_b32_e64 v74, v74, 0, vcc
	v_cmp_lt_u32_e32 vcc, 15, v74
	v_lshlrev_b32_e32 v75, 11, v73
	v_lshl_add_u32 v75, v74, 4, v75
	v_lshlrev_b32_e32 v76, 7, v73
	v_lshl_add_u32 v76, v74, 4, v76
	v_add_u32_e32 v76, 0xffffff00, v76
	v_cndmask_b32_e32 v75, v75, v76, vcc
	v_cndmask_b32_e32 v76, v68, v70, vcc
	v_cndmask_b32_e32 v77, v69, v71, vcc
	v_cndmask_b32_e32 v136, v79, v78, vcc
	v_add_co_u32_e32 v118, vcc, v76, v75
	s_nop 1
	v_addc_co_u32_e32 v119, vcc, 0, v77, vcc
	v_add_u32_e32 v72, 1536, v1
	v_mul_hi_u32 v73, v72, s99
	v_mul_u32_u24_e32 v74, 25, v73
	v_sub_u32_e32 v74, v72, v74
	v_cmp_eq_u32_e32 vcc, 24, v74
	s_nop 1
	v_cndmask_b32_e64 v74, v74, 0, vcc
	v_cmp_lt_u32_e32 vcc, 15, v74
	v_lshlrev_b32_e32 v75, 11, v73
	v_lshl_add_u32 v75, v74, 4, v75
	v_lshlrev_b32_e32 v76, 7, v73
	v_lshl_add_u32 v76, v74, 4, v76
	v_add_u32_e32 v76, 0xffffff00, v76
	v_cndmask_b32_e32 v75, v75, v76, vcc
	v_cndmask_b32_e32 v76, v68, v70, vcc
	v_cndmask_b32_e32 v77, v69, v71, vcc
	v_cndmask_b32_e32 v137, v79, v78, vcc
	v_add_co_u32_e32 v120, vcc, v76, v75
	s_nop 1
	v_addc_co_u32_e32 v121, vcc, 0, v77, vcc
	s_lshl_b32 s99, s0, 5
	s_mov_b32 m0, s99
	s_nop 0
	global_load_lds_dwordx4 v[106:107], off
	s_add_i32 m0, s99, 0x2000
	s_nop 0
	global_load_lds_dwordx4 v[108:109], off
	s_add_i32 m0, s99, 0x4000
	s_nop 0
	global_load_lds_dwordx4 v[118:119], off
	s_cmp_lg_u32 s0, 0
	s_cbranch_scc1 .Lkd_p_skip
	s_add_i32 m0, s99, 0x6000
	s_nop 0
	global_load_lds_dwordx4 v[120:121], off
.Lkd_p_skip:
	v_add_co_u32_e32 v106, vcc, v106, v134
	s_nop 1
	v_addc_co_u32_e32 v107, vcc, 0, v107, vcc
	v_add_co_u32_e32 v108, vcc, v108, v135
	s_nop 1
	v_addc_co_u32_e32 v109, vcc, 0, v109, vcc
	v_add_co_u32_e32 v118, vcc, v118, v136
	s_nop 1
	v_addc_co_u32_e32 v119, vcc, 0, v119, vcc
	v_add_co_u32_e32 v120, vcc, v120, v137
	s_nop 1
	v_addc_co_u32_e32 v121, vcc, 0, v121, vcc
	global_load_dwordx4 v[158:161], v[206:207], off
	global_load_dwordx4 v[162:165], v[208:209], off
	global_load_dwordx4 v[98:101], v[2:3], off
	global_load_dwordx4 v[102:105], v[2:3], off offset:32
	global_load_dwordx4 v[110:113], v[2:3], off offset:64
	global_load_dwordx4 v[114:117], v[2:3], off offset:96
	global_load_dwordx4 v[122:125], v[2:3], off offset:128
	global_load_dwordx4 v[126:129], v[2:3], off offset:160
	global_load_dwordx4 v[130:133], v[2:3], off offset:192
	global_load_dwordx4 v[138:141], v[2:3], off offset:224
	global_load_dwordx4 v[142:145], v[2:3], off offset:256
	global_load_dwordx4 v[146:149], v[2:3], off offset:288
	global_load_dwordx4 v[150:153], v[2:3], off offset:320
	global_load_dwordx4 v[154:157], v[2:3], off offset:352
	v_mov_b32_e32 v14, v0
	v_mov_b32_e32 v15, v0
	v_mov_b32_e32 v1, v0
	v_mov_b32_e32 v2, v0
	v_mov_b32_e32 v3, v0
	v_mov_b32_e32 v4, v0
	v_mov_b32_e32 v5, v0
	v_mov_b32_e32 v6, v0
	v_mov_b32_e32 v7, v0
	v_mov_b32_e32 v8, v0
	v_mov_b32_e32 v9, v0
	v_mov_b32_e32 v10, v0
	v_mov_b32_e32 v11, v0
	v_mov_b32_e32 v12, v0
	v_mov_b32_e32 v13, v0
	v_mov_b64_e32 v[64:65], v[14:15]
	v_mov_b64_e32 v[48:49], v[14:15]
	v_mov_b64_e32 v[32:33], v[14:15]
	s_lshl_b32 s15, s24, 2
	v_mov_b64_e32 v[62:63], v[12:13]
	v_mov_b64_e32 v[60:61], v[10:11]
	v_mov_b64_e32 v[58:59], v[8:9]
	v_mov_b64_e32 v[56:57], v[6:7]
	v_mov_b64_e32 v[54:55], v[4:5]
	v_mov_b64_e32 v[52:53], v[2:3]
	v_mov_b64_e32 v[50:51], v[0:1]
	v_mov_b64_e32 v[46:47], v[12:13]
	v_mov_b64_e32 v[44:45], v[10:11]
	v_mov_b64_e32 v[42:43], v[8:9]
	v_mov_b64_e32 v[40:41], v[6:7]
	v_mov_b64_e32 v[38:39], v[4:5]
	v_mov_b64_e32 v[36:37], v[2:3]
	v_mov_b64_e32 v[34:35], v[0:1]
	v_mov_b64_e32 v[30:31], v[12:13]
	v_mov_b64_e32 v[28:29], v[10:11]
	v_mov_b64_e32 v[26:27], v[8:9]
	v_mov_b64_e32 v[24:25], v[6:7]
	v_mov_b64_e32 v[22:23], v[4:5]
	v_mov_b64_e32 v[20:21], v[2:3]
	v_mov_b64_e32 v[18:19], v[0:1]
	v_mov_b64_e32 v[16:17], v[14:15]
	s_mov_b32 s6, 0
	v_mov_b32_e32 v229, 0xf149f2ca
	s_add_i32 s15, s15, 4
	s_add_i32 s24, s25, 0x100
	s_or_b32 s25, s14, 31
	v_or_b32_e32 v228, s14, v166
	v_mov_b32_e32 v227, 0
	s_mov_b32 s26, 1
	v_mov_b64_e32 v[220:221], v[216:217]
	v_mov_b64_e32 v[222:223], v[214:215]
	v_mov_b64_e32 v[224:225], v[212:213]
	v_mov_b64_e32 v[14:15], v[12:13]
	v_mov_b64_e32 v[12:13], v[10:11]
	v_mov_b64_e32 v[10:11], v[8:9]
	v_mov_b64_e32 v[8:9], v[6:7]
	v_mov_b64_e32 v[6:7], v[4:5]
	v_mov_b64_e32 v[4:5], v[2:3]
	v_mov_b64_e32 v[2:3], v[0:1]
	s_waitcnt vmcnt(0)
	ds_write2_b64 v187, v[158:159], v[160:161] offset1:1
	ds_write2_b64 v195, v[162:163], v[164:165] offset1:1
	s_waitcnt lgkmcnt(0)
	s_barrier
	s_branch .LBB0_1450

; #define AT_LOAD(t) do { const bf16_t* kn_ = knp + (size_t)(t) * 65536; kreg[0] = *(const u32x4*)(kn_); kreg[1] = *(const u32x4*)(kn_ + 64); kreg[2] = *(const u32x4*)(krp + (size_t)(t) * 4096); \
;                         const bf16_t* vt_ = vtp + (size_t)(t) * 65536; vreg[0] = *(const u32x4*)(vt_); vreg[1] = *(const u32x4*)(vt_ + 4096); } while (0)
; DI void attn_phase(ldsp lds, const bf16_t* Q, const bf16_t* KN, const bf16_t* KR, const bf16_t* VT, bf16_t* O, int vcu, int G) {
;     ...
;                 if (t + 1 < ntiles) AT_LOAD(t + 1);
.LBB0_1453:
	s_and_b32 s99, s26, 1
	s_mul_i32 s99, s99, 0xa800
	s_lshl_b32 s98, s0, 5
	s_add_i32 s99, s99, s98
	s_mov_b32 m0, s99
	s_nop 0
	global_load_lds_dwordx4 v[106:107], off
	s_add_i32 m0, s99, 0x2000
	s_nop 0
	global_load_lds_dwordx4 v[108:109], off
	s_add_i32 m0, s99, 0x4000
	s_nop 0
	global_load_lds_dwordx4 v[118:119], off
	s_cmp_lg_u32 s0, 0
	s_cbranch_scc1 .Lkd_l_skip
	s_add_i32 m0, s99, 0x6000
	s_nop 0
	global_load_lds_dwordx4 v[120:121], off
.Lkd_l_skip:
	v_add_co_u32_e32 v106, vcc, v106, v134
	s_nop 1
	v_addc_co_u32_e32 v107, vcc, 0, v107, vcc
	v_add_co_u32_e32 v108, vcc, v108, v135
	s_nop 1
	v_addc_co_u32_e32 v109, vcc, 0, v109, vcc
	v_add_co_u32_e32 v118, vcc, v118, v136
	s_nop 1
	v_addc_co_u32_e32 v119, vcc, 0, v119, vcc
	v_add_co_u32_e32 v120, vcc, v120, v137
	s_nop 1
	v_addc_co_u32_e32 v121, vcc, 0, v121, vcc
	v_lshl_add_u64 v[66:67], v[220:221], 0, v[176:177]
	v_add_co_u32_e32 v68, vcc, 0x38020000, v66
	s_nop 1
	v_addc_co_u32_e32 v69, vcc, 0, v67, vcc
	v_add_co_u32_e32 v66, vcc, 0x38022000, v66
	s_nop 1
	v_addc_co_u32_e32 v67, vcc, 0, v67, vcc
	global_load_dwordx4 v[158:161], v[68:69], off
	global_load_dwordx4 v[162:165], v[66:67], off
	s_add_i32 s27, s26, -1
	s_and_b32 s27, s27, 1
	s_cmp_gt_i32 s6, s25
	s_cbranch_scc1 .LBB0_1452

; #define AT_STORE(buf) do { ldsp base_ = lds + (buf) * AT_BUF; *(LAS u32x4*)(base_ + kdst) = kreg[0]; *(LAS u32x4*)(base_ + kdst + 128) = kreg[1]; *(LAS u32x4*)(base_ + kdst + 256) = kreg[2]; \
;                            lds_w8x2(base_ + vdst, vreg[0]); lds_w8x2(base_ + vdst + 64 * AT_VP, vreg[1]); } while (0)
; DI void attn_phase(ldsp lds, const bf16_t* Q, const bf16_t* KN, const bf16_t* KR, const bf16_t* VT, bf16_t* O, int vcu, int G) {
;     ...
;                 if (t + 1 < ntiles) AT_STORE(buf ^ 1);
;                 __syncthreads();
.LBB0_1459:
	s_xor_b32 s16, s27, 1
	s_mul_i32 s16, s16, 0xa800
	s_add_i32 s16, s16, 0
	v_add_u32_e32 v1, s16, v186
	v_add_u32_e32 v66, 0x6400, v1
	v_add_u32_e32 v1, 0x8600, v1
	s_waitcnt vmcnt(1)
	ds_write2_b64 v66, v[158:159], v[160:161] offset1:1
	s_waitcnt vmcnt(0)
	ds_write2_b64 v1, v[162:163], v[164:165] offset1:1
	s_branch .LBB0_1449
